# same as previous best but s_sleep 1 instead of 2 in the load path of waves 4-7
# speedup vs baseline: 1.0088x; 1.0023x over previous
; #define PG8_STAGE(bufoff, gbase, voff) do { _Pragma("unroll") for (int _i = 0; _i < 2; ++_i) \
;         __builtin_amdgcn_global_load_lds((const unsigned*)((const char*)(gbase) + (voff)[_i]), (PG8_LAS unsigned*)(lds + (bufoff) + ldsw + _i * 8192), 16, 0, 0); } while (0)
; #define PG8_LDA(dst, b, h) do { _Pragma("unroll") for (int m = 0; m < 4; ++m) _Pragma("unroll") for (int k = 0; k < 2; ++k) dst[m][k] = *(const PG8_LAS bf16x8*)(lds + PG8_SA(b, h) + aoff + m * 2048 + k * 1024); } while (0)
; #define PG8_LDB(dst, b, h) do { _Pragma("unroll") for (int n = 0; n < 2; ++n) _Pragma("unroll") for (int k = 0; k < 2; ++k) dst[n][k] = *(const PG8_LAS bf16x8*)(lds + PG8_SB(b, h) + boff + n * 2048 + k * 1024); } while (0)
; #define PG8_MMA(ai, bj, At, Bt) do { __builtin_amdgcn_s_setprio(1); _Pragma("unroll") for (int m = 0; m < 4; ++m) _Pragma("unroll") for (int n = 0; n < 2; ++n) _Pragma("unroll") for (int k = 0; k < 2; ++k) \
;         acc[ai][bj][m][n] = __builtin_amdgcn_mfma_f32_16x16x32_bf16(Bt[n][k], At[m][k], acc[ai][bj][m][n], 0, 0, 0); __builtin_amdgcn_s_setprio(0); } while (0)
; #define PG8_WAIT_V(n) asm volatile("s_waitcnt vmcnt(" #n ")" ::: "memory")
; #define PG8_WAIT_L(n) asm volatile("s_waitcnt lgkmcnt(" #n ")" ::: "memory")
; #define PG8_BAR __builtin_amdgcn_s_barrier()
; #define PG8_SCHED __builtin_amdgcn_sched_barrier(0)
; template <class Epi, class Sched, bool ALIGN_EPI = false, bool SP2 = false>
; __device__ __forceinline__ void gemm_phase(PG8_LAS unsigned char* lds, const Gemm g, const Sched& S, const Epi& E) {
;     ...
;             PG8_LDB(B0, 0, 0); PG8_LDB(B1, 0, 1); PG8_SCHED; PG8_LDA(At, 0, 0); PG8_STAGE(PG8_SA(1, 1), a1 + hstep, voffA);
;             PG8_WAIT_V(8); PG8_WAIT_L(0); PG8_BAR; PG8_MMA(0, 0, At, B0); PG8_MMA(0, 1, At, B1); PG8_BAR; PG8_SCHED;
;             PG8_LDA(At, 0, 1); PG8_STAGE(PG8_SB(0, 0), b2, voffB); PG8_STAGE(PG8_SB(0, 1), b2 + hstep, voffB); PG8_STAGE(PG8_SA(0, 0), a2, voffA);
;             PG8_WAIT_V(8); PG8_WAIT_L(0); PG8_BAR; PG8_MMA(1, 0, At, B0); PG8_MMA(1, 1, At, B1); PG8_BAR; PG8_SCHED;
.Lip_h1:
	ds_read_b128 v[150:153], v169
	ds_read_b128 v[154:157], v169 offset:1024
	ds_read_b128 v[158:161], v169 offset:2048
	ds_read_b128 v[162:165], v169 offset:3072
	ds_read_b128 v[174:177], v170
	ds_read_b128 v[178:181], v170 offset:1024
	ds_read_b128 v[182:185], v170 offset:2048
	ds_read_b128 v[186:189], v170 offset:3072
	s_add_u32 s0, s88, 0xfff00080
	s_addc_u32 s1, s89, -1
	s_cmp_eq_u32 s23, 60
	s_cselect_b32 s93, s51, s1
	s_cselect_b32 s92, s50, s0
	s_cselect_b32 s91, s53, s21
	s_cselect_b32 s90, s52, s9
	ds_read_b128 v[190:193], v171
	ds_read_b128 v[196:199], v171 offset:1024
	ds_read_b128 v[200:203], v171 offset:2048
	ds_read_b128 v[204:207], v171 offset:3072
	ds_read_b128 v[208:211], v171 offset:4096
	ds_read_b128 v[212:215], v171 offset:5120
	ds_read_b128 v[220:223], v171 offset:6144
	ds_read_b128 v[224:227], v171 offset:7168
	s_add_u32 s0, s88, 0xfff00000
	s_addc_u32 s1, s89, -1
	s_add_i32 m0, s27, 0x8000
	s_nop 0
	global_load_lds_dwordx4 v134, s[0:1]
	s_add_i32 m0, s27, 0xa000
	s_nop 0
	global_load_lds_dwordx4 v138, s[0:1]
	s_add_i32 m0, s27, 0xc000
	s_nop 0
	global_load_lds_dwordx4 v134, s[88:89]
	s_add_i32 m0, s27, 0xe000
	s_nop 0
	global_load_lds_dwordx4 v138, s[88:89]
	s_sleep 1
	s_waitcnt lgkmcnt(0)
	s_waitcnt vmcnt(8)
	s_barrier
	s_setprio 2
	v_mfma_f32_16x16x32_bf16 v[38:41], v[150:153], v[190:193], v[38:41]
	v_mfma_f32_16x16x32_bf16 v[30:33], v[158:161], v[190:193], v[30:33]
	v_mfma_f32_16x16x32_bf16 v[130:133], v[150:153], v[200:203], v[130:133]
	v_mfma_f32_16x16x32_bf16 v[126:129], v[158:161], v[200:203], v[126:129]
	v_mfma_f32_16x16x32_bf16 v[114:117], v[150:153], v[208:211], v[114:117]
	v_mfma_f32_16x16x32_bf16 v[110:113], v[158:161], v[208:211], v[110:113]
	v_mfma_f32_16x16x32_bf16 v[98:101], v[150:153], v[220:223], v[98:101]
	v_mfma_f32_16x16x32_bf16 v[94:97], v[158:161], v[220:223], v[94:97]
	v_mfma_f32_16x16x32_bf16 v[38:41], v[154:157], v[196:199], v[38:41]
	v_mfma_f32_16x16x32_bf16 v[30:33], v[162:165], v[196:199], v[30:33]
	v_mfma_f32_16x16x32_bf16 v[130:133], v[154:157], v[204:207], v[130:133]
	v_mfma_f32_16x16x32_bf16 v[126:129], v[162:165], v[204:207], v[126:129]
	v_mfma_f32_16x16x32_bf16 v[114:117], v[154:157], v[212:215], v[114:117]
	v_mfma_f32_16x16x32_bf16 v[110:113], v[162:165], v[212:215], v[110:113]
	v_mfma_f32_16x16x32_bf16 v[98:101], v[154:157], v[224:227], v[98:101]
	v_mfma_f32_16x16x32_bf16 v[94:97], v[162:165], v[224:227], v[94:97]
	v_mfma_f32_16x16x32_bf16 v[50:53], v[174:177], v[190:193], v[50:53]
	v_mfma_f32_16x16x32_bf16 v[46:49], v[182:185], v[190:193], v[46:49]
	v_mfma_f32_16x16x32_bf16 v[122:125], v[174:177], v[200:203], v[122:125]
	v_mfma_f32_16x16x32_bf16 v[118:121], v[182:185], v[200:203], v[118:121]
	v_mfma_f32_16x16x32_bf16 v[106:109], v[174:177], v[208:211], v[106:109]
	v_mfma_f32_16x16x32_bf16 v[102:105], v[182:185], v[208:211], v[102:105]
	v_mfma_f32_16x16x32_bf16 v[90:93], v[174:177], v[220:223], v[90:93]
	v_mfma_f32_16x16x32_bf16 v[86:89], v[182:185], v[220:223], v[86:89]
	v_mfma_f32_16x16x32_bf16 v[50:53], v[178:181], v[196:199], v[50:53]
	v_mfma_f32_16x16x32_bf16 v[46:49], v[186:189], v[196:199], v[46:49]
	v_mfma_f32_16x16x32_bf16 v[122:125], v[178:181], v[204:207], v[122:125]
	v_mfma_f32_16x16x32_bf16 v[118:121], v[186:189], v[204:207], v[118:121]
	v_mfma_f32_16x16x32_bf16 v[106:109], v[178:181], v[212:215], v[106:109]
	v_mfma_f32_16x16x32_bf16 v[102:105], v[186:189], v[212:215], v[102:105]
	v_mfma_f32_16x16x32_bf16 v[90:93], v[178:181], v[224:227], v[90:93]
	v_mfma_f32_16x16x32_bf16 v[86:89], v[186:189], v[224:227], v[86:89]
	s_setprio 0
	ds_read_b128 v[190:193], v171 offset:16384
	ds_read_b128 v[196:199], v171 offset:17408
	ds_read_b128 v[200:203], v171 offset:18432
	ds_read_b128 v[204:207], v171 offset:19456
	ds_read_b128 v[208:211], v171 offset:20480
	ds_read_b128 v[212:215], v171 offset:21504
	ds_read_b128 v[220:223], v171 offset:22528
	ds_read_b128 v[224:227], v171 offset:23552
	s_add_u32 vcc_lo, s90, 0x100000
	s_addc_u32 vcc_hi, s91, 0
	s_add_i32 m0, s27, 0x10000
	s_nop 0
	global_load_lds_dwordx4 v136, s[90:91]
	s_add_i32 m0, s27, 0x12000
	s_nop 0
	global_load_lds_dwordx4 v140, s[90:91]
	s_add_i32 m0, s27, 0x14000
	s_nop 0
	global_load_lds_dwordx4 v136, vcc
	s_add_i32 m0, s27, 0x16000
	s_nop 0
	global_load_lds_dwordx4 v140, vcc
	s_sleep 1
	s_waitcnt lgkmcnt(0)
	s_waitcnt vmcnt(6)
	s_barrier
; #define PG8_STAGE(bufoff, gbase, voff) do { _Pragma("unroll") for (int _i = 0; _i < 2; ++_i) \
;         __builtin_amdgcn_global_load_lds((const unsigned*)((const char*)(gbase) + (voff)[_i]), (PG8_LAS unsigned*)(lds + (bufoff) + ldsw + _i * 8192), 16, 0, 0); } while (0)
; #define PG8_LDA(dst, b, h) do { _Pragma("unroll") for (int m = 0; m < 4; ++m) _Pragma("unroll") for (int k = 0; k < 2; ++k) dst[m][k] = *(const PG8_LAS bf16x8*)(lds + PG8_SA(b, h) + aoff + m * 2048 + k * 1024); } while (0)
; #define PG8_LDB(dst, b, h) do { _Pragma("unroll") for (int n = 0; n < 2; ++n) _Pragma("unroll") for (int k = 0; k < 2; ++k) dst[n][k] = *(const PG8_LAS bf16x8*)(lds + PG8_SB(b, h) + boff + n * 2048 + k * 1024); } while (0)
; #define PG8_MMA(ai, bj, At, Bt) do { __builtin_amdgcn_s_setprio(1); _Pragma("unroll") for (int m = 0; m < 4; ++m) _Pragma("unroll") for (int n = 0; n < 2; ++n) _Pragma("unroll") for (int k = 0; k < 2; ++k) \
;         acc[ai][bj][m][n] = __builtin_amdgcn_mfma_f32_16x16x32_bf16(Bt[n][k], At[m][k], acc[ai][bj][m][n], 0, 0, 0); __builtin_amdgcn_s_setprio(0); } while (0)
; #define PG8_WAIT_V(n) asm volatile("s_waitcnt vmcnt(" #n ")" ::: "memory")
; #define PG8_WAIT_L(n) asm volatile("s_waitcnt lgkmcnt(" #n ")" ::: "memory")
; #define PG8_BAR __builtin_amdgcn_s_barrier()
; #define PG8_SCHED __builtin_amdgcn_sched_barrier(0)
; template <class Epi, class Sched, bool ALIGN_EPI = false, bool SP2 = false>
; __device__ __forceinline__ void gemm_phase(PG8_LAS unsigned char* lds, const Gemm g, const Sched& S, const Epi& E) {
;     ...
;             PG8_WAIT_V(8); PG8_WAIT_L(0); PG8_BAR; PG8_MMA(0, 0, At, B0); PG8_MMA(0, 1, At, B1); PG8_BAR; PG8_SCHED;
;             PG8_LDA(At, 0, 1); PG8_STAGE(PG8_SB(0, 0), b2, voffB); PG8_STAGE(PG8_SB(0, 1), b2 + hstep, voffB); PG8_STAGE(PG8_SA(0, 0), a2, voffA);
;             PG8_WAIT_V(8); PG8_WAIT_L(0); PG8_BAR; PG8_MMA(1, 0, At, B0); PG8_MMA(1, 1, At, B1); PG8_BAR; PG8_SCHED;
;             PG8_LDB(B0, 1, 0); PG8_LDB(B1, 1, 1); PG8_SCHED; PG8_LDA(At, 1, 0); PG8_STAGE(PG8_SA(0, 1), a2 + hstep, voffA);
;             PG8_WAIT_V(8); PG8_WAIT_L(0); PG8_BAR; PG8_MMA(0, 0, At, B0); PG8_MMA(0, 1, At, B1); PG8_BAR; PG8_SCHED;
	s_setprio 2
	v_mfma_f32_16x16x32_bf16 v[82:85], v[150:153], v[190:193], v[82:85]
	v_mfma_f32_16x16x32_bf16 v[78:81], v[158:161], v[190:193], v[78:81]
	v_mfma_f32_16x16x32_bf16 v[66:69], v[150:153], v[200:203], v[66:69]
	v_mfma_f32_16x16x32_bf16 v[62:65], v[158:161], v[200:203], v[62:65]
	v_mfma_f32_16x16x32_bf16 v[42:45], v[150:153], v[208:211], v[42:45]
	v_mfma_f32_16x16x32_bf16 v[34:37], v[158:161], v[208:211], v[34:37]
	v_mfma_f32_16x16x32_bf16 v[18:21], v[150:153], v[220:223], v[18:21]
	v_mfma_f32_16x16x32_bf16 v[14:17], v[158:161], v[220:223], v[14:17]
	v_mfma_f32_16x16x32_bf16 v[82:85], v[154:157], v[196:199], v[82:85]
	v_mfma_f32_16x16x32_bf16 v[78:81], v[162:165], v[196:199], v[78:81]
	v_mfma_f32_16x16x32_bf16 v[66:69], v[154:157], v[204:207], v[66:69]
	v_mfma_f32_16x16x32_bf16 v[62:65], v[162:165], v[204:207], v[62:65]
	v_mfma_f32_16x16x32_bf16 v[42:45], v[154:157], v[212:215], v[42:45]
	v_mfma_f32_16x16x32_bf16 v[34:37], v[162:165], v[212:215], v[34:37]
	v_mfma_f32_16x16x32_bf16 v[18:21], v[154:157], v[224:227], v[18:21]
	v_mfma_f32_16x16x32_bf16 v[14:17], v[162:165], v[224:227], v[14:17]
	v_mfma_f32_16x16x32_bf16 v[74:77], v[174:177], v[190:193], v[74:77]
	v_mfma_f32_16x16x32_bf16 v[70:73], v[182:185], v[190:193], v[70:73]
	v_mfma_f32_16x16x32_bf16 v[58:61], v[174:177], v[200:203], v[58:61]
	v_mfma_f32_16x16x32_bf16 v[54:57], v[182:185], v[200:203], v[54:57]
	v_mfma_f32_16x16x32_bf16 v[26:29], v[174:177], v[208:211], v[26:29]
	v_mfma_f32_16x16x32_bf16 v[22:25], v[182:185], v[208:211], v[22:25]
	v_mfma_f32_16x16x32_bf16 v[10:13], v[174:177], v[220:223], v[10:13]
	v_mfma_f32_16x16x32_bf16 v[4:7], v[182:185], v[220:223], v[6:9]
	v_mfma_f32_16x16x32_bf16 v[74:77], v[178:181], v[196:199], v[74:77]
	v_mfma_f32_16x16x32_bf16 v[70:73], v[186:189], v[196:199], v[70:73]
	v_mfma_f32_16x16x32_bf16 v[58:61], v[178:181], v[204:207], v[58:61]
	v_mfma_f32_16x16x32_bf16 v[54:57], v[186:189], v[204:207], v[54:57]
	v_mfma_f32_16x16x32_bf16 v[26:29], v[178:181], v[212:215], v[26:29]
	v_mfma_f32_16x16x32_bf16 v[22:25], v[186:189], v[212:215], v[22:25]
	v_mfma_f32_16x16x32_bf16 v[10:13], v[178:181], v[224:227], v[10:13]
	v_mfma_f32_16x16x32_bf16 v[4:7], v[186:189], v[224:227], v[4:7]
	s_setprio 0
	s_add_i32 s0, 0, 0x18000
	v_add_u32_e32 v3, s0, v167
	s_add_i32 s1, 0, 0x1c000
	ds_read_b128 v[150:153], v3
	ds_read_b128 v[154:157], v3 offset:1024
	ds_read_b128 v[158:161], v3 offset:2048
	ds_read_b128 v[162:165], v3 offset:3072
	v_add_u32_e32 v3, s1, v167
	ds_read_b128 v[174:177], v3
	ds_read_b128 v[178:181], v3 offset:1024
	ds_read_b128 v[182:185], v3 offset:2048
	ds_read_b128 v[186:189], v3 offset:3072
	ds_read_b128 v[190:193], v171 offset:32768
	ds_read_b128 v[196:199], v171 offset:33792
	ds_read_b128 v[200:203], v171 offset:34816
	ds_read_b128 v[204:207], v171 offset:35840
	ds_read_b128 v[208:211], v171 offset:36864
	ds_read_b128 v[212:215], v171 offset:37888
	ds_read_b128 v[220:223], v171 offset:38912
	ds_read_b128 v[224:227], v171 offset:39936
	s_add_u32 vcc_lo, s92, 0x100000
	s_addc_u32 vcc_hi, s93, 0
	s_mov_b32 m0, s27
	s_nop 0
	global_load_lds_dwordx4 v134, s[92:93]
	s_add_i32 m0, s27, 0x2000
	s_nop 0
	global_load_lds_dwordx4 v138, s[92:93]
	s_add_i32 m0, s27, 0x4000
	s_nop 0
	global_load_lds_dwordx4 v134, vcc
	s_add_i32 m0, s27, 0x6000
	s_nop 0
	global_load_lds_dwordx4 v138, vcc
	s_sleep 1
	s_waitcnt lgkmcnt(0)
	s_waitcnt vmcnt(8)
	s_barrier
; #define PG8_STAGE(bufoff, gbase, voff) do { _Pragma("unroll") for (int _i = 0; _i < 2; ++_i) \
;         __builtin_amdgcn_global_load_lds((const unsigned*)((const char*)(gbase) + (voff)[_i]), (PG8_LAS unsigned*)(lds + (bufoff) + ldsw + _i * 8192), 16, 0, 0); } while (0)
; #define PG8_LDA(dst, b, h) do { _Pragma("unroll") for (int m = 0; m < 4; ++m) _Pragma("unroll") for (int k = 0; k < 2; ++k) dst[m][k] = *(const PG8_LAS bf16x8*)(lds + PG8_SA(b, h) + aoff + m * 2048 + k * 1024); } while (0)
; #define PG8_LDB(dst, b, h) do { _Pragma("unroll") for (int n = 0; n < 2; ++n) _Pragma("unroll") for (int k = 0; k < 2; ++k) dst[n][k] = *(const PG8_LAS bf16x8*)(lds + PG8_SB(b, h) + boff + n * 2048 + k * 1024); } while (0)
; #define PG8_MMA(ai, bj, At, Bt) do { __builtin_amdgcn_s_setprio(1); _Pragma("unroll") for (int m = 0; m < 4; ++m) _Pragma("unroll") for (int n = 0; n < 2; ++n) _Pragma("unroll") for (int k = 0; k < 2; ++k) \
;         acc[ai][bj][m][n] = __builtin_amdgcn_mfma_f32_16x16x32_bf16(Bt[n][k], At[m][k], acc[ai][bj][m][n], 0, 0, 0); __builtin_amdgcn_s_setprio(0); } while (0)
; #define PG8_WAIT_V(n) asm volatile("s_waitcnt vmcnt(" #n ")" ::: "memory")
; #define PG8_WAIT_L(n) asm volatile("s_waitcnt lgkmcnt(" #n ")" ::: "memory")
; #define PG8_BAR __builtin_amdgcn_s_barrier()
; #define PG8_SCHED __builtin_amdgcn_sched_barrier(0)
; template <class Epi, class Sched, bool ALIGN_EPI = false, bool SP2 = false>
; __device__ __forceinline__ void gemm_phase(PG8_LAS unsigned char* lds, const Gemm g, const Sched& S, const Epi& E) {
;     ...
;             PG8_LDB(B0, 1, 0); PG8_LDB(B1, 1, 1); PG8_SCHED; PG8_LDA(At, 1, 0); PG8_STAGE(PG8_SA(0, 1), a2 + hstep, voffA);
;             PG8_WAIT_V(8); PG8_WAIT_L(0); PG8_BAR; PG8_MMA(0, 0, At, B0); PG8_MMA(0, 1, At, B1); PG8_BAR; PG8_SCHED;
;             PG8_LDA(At, 1, 1); PG8_STAGE(PG8_SB(1, 0), b3, voffB); PG8_STAGE(PG8_SB(1, 1), b3 + hstep, voffB); PG8_STAGE(PG8_SA(1, 0), a3, voffA);
;             PG8_WAIT_V(8); PG8_WAIT_L(0); PG8_BAR; PG8_MMA(1, 0, At, B0); PG8_MMA(1, 1, At, B1); PG8_BAR; PG8_SCHED;
	s_setprio 2
	v_mfma_f32_16x16x32_bf16 v[38:41], v[150:153], v[190:193], v[38:41]
	v_mfma_f32_16x16x32_bf16 v[30:33], v[158:161], v[190:193], v[30:33]
	v_mfma_f32_16x16x32_bf16 v[130:133], v[150:153], v[200:203], v[130:133]
	v_mfma_f32_16x16x32_bf16 v[126:129], v[158:161], v[200:203], v[126:129]
	v_mfma_f32_16x16x32_bf16 v[114:117], v[150:153], v[208:211], v[114:117]
	v_mfma_f32_16x16x32_bf16 v[110:113], v[158:161], v[208:211], v[110:113]
	v_mfma_f32_16x16x32_bf16 v[98:101], v[150:153], v[220:223], v[98:101]
	v_mfma_f32_16x16x32_bf16 v[94:97], v[158:161], v[220:223], v[94:97]
	v_mfma_f32_16x16x32_bf16 v[38:41], v[154:157], v[196:199], v[38:41]
	v_mfma_f32_16x16x32_bf16 v[30:33], v[162:165], v[196:199], v[30:33]
	v_mfma_f32_16x16x32_bf16 v[130:133], v[154:157], v[204:207], v[130:133]
	v_mfma_f32_16x16x32_bf16 v[126:129], v[162:165], v[204:207], v[126:129]
	v_mfma_f32_16x16x32_bf16 v[114:117], v[154:157], v[212:215], v[114:117]
	v_mfma_f32_16x16x32_bf16 v[110:113], v[162:165], v[212:215], v[110:113]
	v_mfma_f32_16x16x32_bf16 v[98:101], v[154:157], v[224:227], v[98:101]
	v_mfma_f32_16x16x32_bf16 v[94:97], v[162:165], v[224:227], v[94:97]
	v_mfma_f32_16x16x32_bf16 v[50:53], v[174:177], v[190:193], v[50:53]
	v_mfma_f32_16x16x32_bf16 v[46:49], v[182:185], v[190:193], v[46:49]
	v_mfma_f32_16x16x32_bf16 v[122:125], v[174:177], v[200:203], v[122:125]
	v_mfma_f32_16x16x32_bf16 v[118:121], v[182:185], v[200:203], v[118:121]
	v_mfma_f32_16x16x32_bf16 v[106:109], v[174:177], v[208:211], v[106:109]
	v_mfma_f32_16x16x32_bf16 v[102:105], v[182:185], v[208:211], v[102:105]
	v_mfma_f32_16x16x32_bf16 v[90:93], v[174:177], v[220:223], v[90:93]
	v_mfma_f32_16x16x32_bf16 v[86:89], v[182:185], v[220:223], v[86:89]
	v_mfma_f32_16x16x32_bf16 v[50:53], v[178:181], v[196:199], v[50:53]
	v_mfma_f32_16x16x32_bf16 v[46:49], v[186:189], v[196:199], v[46:49]
	v_mfma_f32_16x16x32_bf16 v[122:125], v[178:181], v[204:207], v[122:125]
	v_mfma_f32_16x16x32_bf16 v[118:121], v[186:189], v[204:207], v[118:121]
	v_mfma_f32_16x16x32_bf16 v[106:109], v[178:181], v[212:215], v[106:109]
	v_mfma_f32_16x16x32_bf16 v[102:105], v[186:189], v[212:215], v[102:105]
	v_mfma_f32_16x16x32_bf16 v[90:93], v[178:181], v[224:227], v[90:93]
	v_mfma_f32_16x16x32_bf16 v[86:89], v[186:189], v[224:227], v[86:89]
	s_setprio 0
	ds_read_b128 v[190:193], v171 offset:49152
	ds_read_b128 v[196:199], v171 offset:50176
	ds_read_b128 v[200:203], v171 offset:51200
	ds_read_b128 v[204:207], v171 offset:52224
	ds_read_b128 v[208:211], v171 offset:53248
	ds_read_b128 v[212:215], v171 offset:54272
	ds_read_b128 v[220:223], v171 offset:55296
	ds_read_b128 v[224:227], v171 offset:56320
	s_add_u32 s0, s90, 0x80
	s_addc_u32 s1, s91, 0
	s_add_u32 vcc_lo, s0, 0x100000
	s_addc_u32 vcc_hi, s1, 0
	s_add_i32 m0, s27, 0x18000
	s_nop 0
	global_load_lds_dwordx4 v136, s[0:1]
	s_add_i32 m0, s27, 0x1a000
	s_nop 0
	global_load_lds_dwordx4 v140, s[0:1]
	s_add_i32 m0, s27, 0x1c000
	s_nop 0
	global_load_lds_dwordx4 v136, vcc
	s_add_i32 m0, s27, 0x1e000
	s_nop 0
	global_load_lds_dwordx4 v140, vcc
	s_sleep 1
	s_waitcnt lgkmcnt(0)
	s_waitcnt vmcnt(6)
	s_barrier
	s_setprio 2
	v_mfma_f32_16x16x32_bf16 v[82:85], v[150:153], v[190:193], v[82:85]
	v_mfma_f32_16x16x32_bf16 v[78:81], v[158:161], v[190:193], v[78:81]
	v_mfma_f32_16x16x32_bf16 v[66:69], v[150:153], v[200:203], v[66:69]
	v_mfma_f32_16x16x32_bf16 v[62:65], v[158:161], v[200:203], v[62:65]
	v_mfma_f32_16x16x32_bf16 v[42:45], v[150:153], v[208:211], v[42:45]
	v_mfma_f32_16x16x32_bf16 v[34:37], v[158:161], v[208:211], v[34:37]
	v_mfma_f32_16x16x32_bf16 v[18:21], v[150:153], v[220:223], v[18:21]
	v_mfma_f32_16x16x32_bf16 v[14:17], v[158:161], v[220:223], v[14:17]
	v_mfma_f32_16x16x32_bf16 v[82:85], v[154:157], v[196:199], v[82:85]
	v_mfma_f32_16x16x32_bf16 v[78:81], v[162:165], v[196:199], v[78:81]
	v_mfma_f32_16x16x32_bf16 v[66:69], v[154:157], v[204:207], v[66:69]
	v_mfma_f32_16x16x32_bf16 v[62:65], v[162:165], v[204:207], v[62:65]
	v_mfma_f32_16x16x32_bf16 v[42:45], v[154:157], v[212:215], v[42:45]
	v_mfma_f32_16x16x32_bf16 v[34:37], v[162:165], v[212:215], v[34:37]
	v_mfma_f32_16x16x32_bf16 v[18:21], v[154:157], v[224:227], v[18:21]
	v_mfma_f32_16x16x32_bf16 v[14:17], v[162:165], v[224:227], v[14:17]
	v_mfma_f32_16x16x32_bf16 v[74:77], v[174:177], v[190:193], v[74:77]
	v_mfma_f32_16x16x32_bf16 v[70:73], v[182:185], v[190:193], v[70:73]
	v_mfma_f32_16x16x32_bf16 v[58:61], v[174:177], v[200:203], v[58:61]
	v_mfma_f32_16x16x32_bf16 v[54:57], v[182:185], v[200:203], v[54:57]
	v_mfma_f32_16x16x32_bf16 v[26:29], v[174:177], v[208:211], v[26:29]
	v_mfma_f32_16x16x32_bf16 v[22:25], v[182:185], v[208:211], v[22:25]
	v_mfma_f32_16x16x32_bf16 v[8:11], v[174:177], v[220:223], v[10:13]
	v_mfma_f32_16x16x32_bf16 v[4:7], v[182:185], v[220:223], v[4:7]
	v_mfma_f32_16x16x32_bf16 v[74:77], v[178:181], v[196:199], v[74:77]
	v_mfma_f32_16x16x32_bf16 v[70:73], v[186:189], v[196:199], v[70:73]
	v_mfma_f32_16x16x32_bf16 v[58:61], v[178:181], v[204:207], v[58:61]
	v_mfma_f32_16x16x32_bf16 v[54:57], v[186:189], v[204:207], v[54:57]
	v_mfma_f32_16x16x32_bf16 v[26:29], v[178:181], v[212:215], v[26:29]
	v_mfma_f32_16x16x32_bf16 v[22:25], v[186:189], v[212:215], v[22:25]
	v_mfma_f32_16x16x32_bf16 v[10:13], v[178:181], v[224:227], v[8:11]
	v_mfma_f32_16x16x32_bf16 v[6:9], v[186:189], v[224:227], v[4:7]
	s_setprio 0
	s_add_i32 s23, s23, 2
	s_add_u32 s88, s88, 0x100
	s_addc_u32 s89, s89, 0
	s_add_u32 s9, s9, 0x100
	s_addc_u32 s21, s21, 0
	s_cmp_gt_u32 s23, 61
	s_cbranch_scc0 .Lip_h1

; #define PG8_STAGE(bufoff, gbase, voff) do { _Pragma("unroll") for (int _i = 0; _i < 2; ++_i) \
;         __builtin_amdgcn_global_load_lds((const unsigned*)((const char*)(gbase) + (voff)[_i]), (PG8_LAS unsigned*)(lds + (bufoff) + ldsw + _i * 8192), 16, 0, 0); } while (0)
; #define PG8_LDA(dst, b, h) do { _Pragma("unroll") for (int m = 0; m < 4; ++m) _Pragma("unroll") for (int k = 0; k < 2; ++k) dst[m][k] = *(const PG8_LAS bf16x8*)(lds + PG8_SA(b, h) + aoff + m * 2048 + k * 1024); } while (0)
; #define PG8_LDB(dst, b, h) do { _Pragma("unroll") for (int n = 0; n < 2; ++n) _Pragma("unroll") for (int k = 0; k < 2; ++k) dst[n][k] = *(const PG8_LAS bf16x8*)(lds + PG8_SB(b, h) + boff + n * 2048 + k * 1024); } while (0)
; #define PG8_MMA(ai, bj, At, Bt) do { __builtin_amdgcn_s_setprio(1); _Pragma("unroll") for (int m = 0; m < 4; ++m) _Pragma("unroll") for (int n = 0; n < 2; ++n) _Pragma("unroll") for (int k = 0; k < 2; ++k) \
;         acc[ai][bj][m][n] = __builtin_amdgcn_mfma_f32_16x16x32_bf16(Bt[n][k], At[m][k], acc[ai][bj][m][n], 0, 0, 0); __builtin_amdgcn_s_setprio(0); } while (0)
; #define PG8_WAIT_V(n) asm volatile("s_waitcnt vmcnt(" #n ")" ::: "memory")
; #define PG8_WAIT_L(n) asm volatile("s_waitcnt lgkmcnt(" #n ")" ::: "memory")
; #define PG8_BAR __builtin_amdgcn_s_barrier()
; #define PG8_SCHED __builtin_amdgcn_sched_barrier(0)
; template <class Epi, class Sched, bool ALIGN_EPI = false, bool SP2 = false>
; __device__ __forceinline__ void gemm_phase(PG8_LAS unsigned char* lds, const Gemm g, const Sched& S, const Epi& E) {
;     ...
;             PG8_LDB(B0, 0, 0); PG8_LDB(B1, 0, 1); PG8_SCHED; PG8_LDA(At, 0, 0); PG8_STAGE(PG8_SA(1, 1), a1 + hstep, voffA);
;             PG8_WAIT_V(8); PG8_WAIT_L(0); PG8_BAR; PG8_MMA(0, 0, At, B0); PG8_MMA(0, 1, At, B1); PG8_BAR; PG8_SCHED;
;             PG8_LDA(At, 0, 1); PG8_STAGE(PG8_SB(0, 0), b2, voffB); PG8_STAGE(PG8_SB(0, 1), b2 + hstep, voffB); PG8_STAGE(PG8_SA(0, 0), a2, voffA);
;             PG8_WAIT_V(8); PG8_WAIT_L(0); PG8_BAR; PG8_MMA(1, 0, At, B0); PG8_MMA(1, 1, At, B1); PG8_BAR; PG8_SCHED;
.Lf1_h1:
	ds_read_b128 v[130:133], v177
	ds_read_b128 v[134:137], v177 offset:1024
	ds_read_b128 v[138:141], v177 offset:2048
	ds_read_b128 v[142:145], v177 offset:3072
	ds_read_b128 v[162:165], v178
	ds_read_b128 v[180:183], v178 offset:1024
	ds_read_b128 v[184:187], v178 offset:2048
	ds_read_b128 v[188:191], v178 offset:3072
	s_add_u32 s40, s36, 0xfff00080
	s_addc_u32 s41, s37, -1
	s_cmp_eq_u32 s58, 60
	s_cselect_b32 s43, s15, s41
	s_cselect_b32 s42, s17, s40
	s_cselect_b32 s41, s54, s57
	s_cselect_b32 s40, s55, s56
	ds_read_b128 v[196:199], v179
	ds_read_b128 v[200:203], v179 offset:1024
	ds_read_b128 v[204:207], v179 offset:2048
	ds_read_b128 v[208:211], v179 offset:3072
	ds_read_b128 v[212:215], v179 offset:4096
	ds_read_b128 v[220:223], v179 offset:5120
	ds_read_b128 v[224:227], v179 offset:6144
	ds_read_b128 v[228:231], v179 offset:7168
	s_add_i32 m0, s24, 0xc000
	s_nop 0
	global_load_lds_dwordx4 v146, s[36:37]
	s_add_i32 m0, s24, 0xe000
	s_nop 0
	global_load_lds_dwordx4 v150, s[36:37]
	s_sleep 1
	s_waitcnt lgkmcnt(0)
	s_waitcnt vmcnt(8)
	s_barrier
	s_setprio 2
	v_mfma_f32_16x16x32_bf16 v[126:129], v[130:133], v[196:199], v[126:129]
	v_mfma_f32_16x16x32_bf16 v[122:125], v[138:141], v[196:199], v[122:125]
	v_mfma_f32_16x16x32_bf16 v[110:113], v[130:133], v[204:207], v[110:113]
	v_mfma_f32_16x16x32_bf16 v[106:109], v[138:141], v[204:207], v[106:109]
	v_mfma_f32_16x16x32_bf16 v[94:97], v[130:133], v[212:215], v[94:97]
	v_mfma_f32_16x16x32_bf16 v[90:93], v[138:141], v[212:215], v[90:93]
	v_mfma_f32_16x16x32_bf16 v[78:81], v[130:133], v[224:227], v[78:81]
	v_mfma_f32_16x16x32_bf16 v[74:77], v[138:141], v[224:227], v[74:77]
	v_mfma_f32_16x16x32_bf16 v[126:129], v[134:137], v[200:203], v[126:129]
	v_mfma_f32_16x16x32_bf16 v[122:125], v[142:145], v[200:203], v[122:125]
	v_mfma_f32_16x16x32_bf16 v[110:113], v[134:137], v[208:211], v[110:113]
	v_mfma_f32_16x16x32_bf16 v[106:109], v[142:145], v[208:211], v[106:109]
	v_mfma_f32_16x16x32_bf16 v[94:97], v[134:137], v[220:223], v[94:97]
	v_mfma_f32_16x16x32_bf16 v[90:93], v[142:145], v[220:223], v[90:93]
	v_mfma_f32_16x16x32_bf16 v[78:81], v[134:137], v[228:231], v[78:81]
	v_mfma_f32_16x16x32_bf16 v[74:77], v[142:145], v[228:231], v[74:77]
	v_mfma_f32_16x16x32_bf16 v[118:121], v[162:165], v[196:199], v[118:121]
	v_mfma_f32_16x16x32_bf16 v[114:117], v[184:187], v[196:199], v[114:117]
	v_mfma_f32_16x16x32_bf16 v[102:105], v[162:165], v[204:207], v[102:105]
	v_mfma_f32_16x16x32_bf16 v[98:101], v[184:187], v[204:207], v[98:101]
	v_mfma_f32_16x16x32_bf16 v[86:89], v[162:165], v[212:215], v[86:89]
	v_mfma_f32_16x16x32_bf16 v[82:85], v[184:187], v[212:215], v[82:85]
	v_mfma_f32_16x16x32_bf16 v[70:73], v[162:165], v[224:227], v[70:73]
	v_mfma_f32_16x16x32_bf16 v[66:69], v[184:187], v[224:227], v[66:69]
	v_mfma_f32_16x16x32_bf16 v[118:121], v[180:183], v[200:203], v[118:121]
	v_mfma_f32_16x16x32_bf16 v[114:117], v[188:191], v[200:203], v[114:117]
	v_mfma_f32_16x16x32_bf16 v[102:105], v[180:183], v[208:211], v[102:105]
	v_mfma_f32_16x16x32_bf16 v[98:101], v[188:191], v[208:211], v[98:101]
	v_mfma_f32_16x16x32_bf16 v[86:89], v[180:183], v[220:223], v[86:89]
	v_mfma_f32_16x16x32_bf16 v[82:85], v[188:191], v[220:223], v[82:85]
	v_mfma_f32_16x16x32_bf16 v[70:73], v[180:183], v[228:231], v[70:73]
	v_mfma_f32_16x16x32_bf16 v[66:69], v[188:191], v[228:231], v[66:69]
	s_setprio 0
	ds_read_b128 v[196:199], v179 offset:16384
	ds_read_b128 v[200:203], v179 offset:17408
	ds_read_b128 v[204:207], v179 offset:18432
	ds_read_b128 v[208:211], v179 offset:19456
	ds_read_b128 v[212:215], v179 offset:20480
	ds_read_b128 v[220:223], v179 offset:21504
	ds_read_b128 v[224:227], v179 offset:22528
	ds_read_b128 v[228:231], v179 offset:23552
	s_add_u32 vcc_lo, s40, 0x100000
	s_addc_u32 vcc_hi, s41, 0
	s_add_i32 m0, s24, 0x10000
	s_nop 0
	global_load_lds_dwordx4 v148, s[40:41]
	s_add_i32 m0, s24, 0x12000
	s_nop 0
	global_load_lds_dwordx4 v152, s[40:41]
	s_add_i32 m0, s24, 0x14000
	s_nop 0
	global_load_lds_dwordx4 v148, vcc
	s_add_i32 m0, s24, 0x16000
	s_nop 0
	global_load_lds_dwordx4 v152, vcc
	s_mov_b32 m0, s24
	s_nop 0
	global_load_lds_dwordx4 v146, s[42:43]
	s_add_i32 m0, s24, 0x2000
	s_nop 0
	global_load_lds_dwordx4 v150, s[42:43]
	s_sleep 1
	s_waitcnt lgkmcnt(0)
	s_waitcnt vmcnt(8)
	s_barrier
; #define PG8_STAGE(bufoff, gbase, voff) do { _Pragma("unroll") for (int _i = 0; _i < 2; ++_i) \
;         __builtin_amdgcn_global_load_lds((const unsigned*)((const char*)(gbase) + (voff)[_i]), (PG8_LAS unsigned*)(lds + (bufoff) + ldsw + _i * 8192), 16, 0, 0); } while (0)
; #define PG8_LDA(dst, b, h) do { _Pragma("unroll") for (int m = 0; m < 4; ++m) _Pragma("unroll") for (int k = 0; k < 2; ++k) dst[m][k] = *(const PG8_LAS bf16x8*)(lds + PG8_SA(b, h) + aoff + m * 2048 + k * 1024); } while (0)
; #define PG8_LDB(dst, b, h) do { _Pragma("unroll") for (int n = 0; n < 2; ++n) _Pragma("unroll") for (int k = 0; k < 2; ++k) dst[n][k] = *(const PG8_LAS bf16x8*)(lds + PG8_SB(b, h) + boff + n * 2048 + k * 1024); } while (0)
; #define PG8_MMA(ai, bj, At, Bt) do { __builtin_amdgcn_s_setprio(1); _Pragma("unroll") for (int m = 0; m < 4; ++m) _Pragma("unroll") for (int n = 0; n < 2; ++n) _Pragma("unroll") for (int k = 0; k < 2; ++k) \
;         acc[ai][bj][m][n] = __builtin_amdgcn_mfma_f32_16x16x32_bf16(Bt[n][k], At[m][k], acc[ai][bj][m][n], 0, 0, 0); __builtin_amdgcn_s_setprio(0); } while (0)
; #define PG8_WAIT_V(n) asm volatile("s_waitcnt vmcnt(" #n ")" ::: "memory")
; #define PG8_WAIT_L(n) asm volatile("s_waitcnt lgkmcnt(" #n ")" ::: "memory")
; #define PG8_BAR __builtin_amdgcn_s_barrier()
; #define PG8_SCHED __builtin_amdgcn_sched_barrier(0)
; template <class Epi, class Sched, bool ALIGN_EPI = false, bool SP2 = false>
; __device__ __forceinline__ void gemm_phase(PG8_LAS unsigned char* lds, const Gemm g, const Sched& S, const Epi& E) {
;     ...
;             PG8_WAIT_V(8); PG8_WAIT_L(0); PG8_BAR; PG8_MMA(0, 0, At, B0); PG8_MMA(0, 1, At, B1); PG8_BAR; PG8_SCHED;
;             PG8_LDA(At, 0, 1); PG8_STAGE(PG8_SB(0, 0), b2, voffB); PG8_STAGE(PG8_SB(0, 1), b2 + hstep, voffB); PG8_STAGE(PG8_SA(0, 0), a2, voffA);
;             PG8_WAIT_V(8); PG8_WAIT_L(0); PG8_BAR; PG8_MMA(1, 0, At, B0); PG8_MMA(1, 1, At, B1); PG8_BAR; PG8_SCHED;
;             PG8_LDB(B0, 1, 0); PG8_LDB(B1, 1, 1); PG8_SCHED; PG8_LDA(At, 1, 0); PG8_STAGE(PG8_SA(0, 1), a2 + hstep, voffA);
;             PG8_WAIT_V(8); PG8_WAIT_L(0); PG8_BAR; PG8_MMA(0, 0, At, B0); PG8_MMA(0, 1, At, B1); PG8_BAR; PG8_SCHED;
	s_setprio 2
	v_mfma_f32_16x16x32_bf16 v[62:65], v[130:133], v[196:199], v[62:65]
	v_mfma_f32_16x16x32_bf16 v[58:61], v[138:141], v[196:199], v[58:61]
	v_mfma_f32_16x16x32_bf16 v[46:49], v[130:133], v[204:207], v[46:49]
	v_mfma_f32_16x16x32_bf16 v[42:45], v[138:141], v[204:207], v[42:45]
	v_mfma_f32_16x16x32_bf16 v[30:33], v[130:133], v[212:215], v[30:33]
	v_mfma_f32_16x16x32_bf16 v[26:29], v[138:141], v[212:215], v[26:29]
	v_mfma_f32_16x16x32_bf16 v[14:17], v[130:133], v[224:227], v[14:17]
	v_mfma_f32_16x16x32_bf16 v[10:13], v[138:141], v[224:227], v[10:13]
	v_mfma_f32_16x16x32_bf16 v[62:65], v[134:137], v[200:203], v[62:65]
	v_mfma_f32_16x16x32_bf16 v[58:61], v[142:145], v[200:203], v[58:61]
	v_mfma_f32_16x16x32_bf16 v[46:49], v[134:137], v[208:211], v[46:49]
	v_mfma_f32_16x16x32_bf16 v[42:45], v[142:145], v[208:211], v[42:45]
	v_mfma_f32_16x16x32_bf16 v[30:33], v[134:137], v[220:223], v[30:33]
	v_mfma_f32_16x16x32_bf16 v[26:29], v[142:145], v[220:223], v[26:29]
	v_mfma_f32_16x16x32_bf16 v[14:17], v[134:137], v[228:231], v[14:17]
	v_mfma_f32_16x16x32_bf16 v[10:13], v[142:145], v[228:231], v[10:13]
	v_mfma_f32_16x16x32_bf16 v[54:57], v[162:165], v[196:199], v[54:57]
	v_mfma_f32_16x16x32_bf16 v[50:53], v[184:187], v[196:199], v[50:53]
	v_mfma_f32_16x16x32_bf16 v[38:41], v[162:165], v[204:207], v[38:41]
	v_mfma_f32_16x16x32_bf16 v[34:37], v[184:187], v[204:207], v[34:37]
	v_mfma_f32_16x16x32_bf16 v[22:25], v[162:165], v[212:215], v[22:25]
	v_mfma_f32_16x16x32_bf16 v[18:21], v[184:187], v[212:215], v[18:21]
	v_mfma_f32_16x16x32_bf16 v[6:9], v[162:165], v[224:227], v[6:9]
	v_mfma_f32_16x16x32_bf16 v[2:5], v[184:187], v[224:227], v[2:5]
	v_mfma_f32_16x16x32_bf16 v[54:57], v[180:183], v[200:203], v[54:57]
	v_mfma_f32_16x16x32_bf16 v[50:53], v[188:191], v[200:203], v[50:53]
	v_mfma_f32_16x16x32_bf16 v[38:41], v[180:183], v[208:211], v[38:41]
	v_mfma_f32_16x16x32_bf16 v[34:37], v[188:191], v[208:211], v[34:37]
	v_mfma_f32_16x16x32_bf16 v[22:25], v[180:183], v[220:223], v[22:25]
	v_mfma_f32_16x16x32_bf16 v[18:21], v[188:191], v[220:223], v[18:21]
	v_mfma_f32_16x16x32_bf16 v[6:9], v[180:183], v[228:231], v[6:9]
	v_mfma_f32_16x16x32_bf16 v[2:5], v[188:191], v[228:231], v[2:5]
	s_setprio 0
	s_add_i32 s59, 0, 0x18000
	s_add_i32 s60, 0, 0x1c000
	v_add_u32_e32 v142, s59, v166
	v_add_u32_e32 v188, s60, v166
	ds_read_b128 v[130:133], v142
	ds_read_b128 v[134:137], v142 offset:1024
	ds_read_b128 v[138:141], v142 offset:2048
	ds_read_b128 v[142:145], v142 offset:3072
	ds_read_b128 v[162:165], v188
	ds_read_b128 v[180:183], v188 offset:1024
	ds_read_b128 v[184:187], v188 offset:2048
	ds_read_b128 v[188:191], v188 offset:3072
	ds_read_b128 v[196:199], v179 offset:32768
	ds_read_b128 v[200:203], v179 offset:33792
	ds_read_b128 v[204:207], v179 offset:34816
	ds_read_b128 v[208:211], v179 offset:35840
	ds_read_b128 v[212:215], v179 offset:36864
	ds_read_b128 v[220:223], v179 offset:37888
	ds_read_b128 v[224:227], v179 offset:38912
	ds_read_b128 v[228:231], v179 offset:39936
	s_add_u32 vcc_lo, s42, 0x100000
	s_addc_u32 vcc_hi, s43, 0
	s_add_i32 m0, s24, 0x4000
	s_nop 0
	global_load_lds_dwordx4 v146, vcc
	s_add_i32 m0, s24, 0x6000
	s_nop 0
	global_load_lds_dwordx4 v150, vcc
	s_sleep 1
	s_waitcnt lgkmcnt(0)
	s_waitcnt vmcnt(8)
	s_barrier
; #define PG8_STAGE(bufoff, gbase, voff) do { _Pragma("unroll") for (int _i = 0; _i < 2; ++_i) \
;         __builtin_amdgcn_global_load_lds((const unsigned*)((const char*)(gbase) + (voff)[_i]), (PG8_LAS unsigned*)(lds + (bufoff) + ldsw + _i * 8192), 16, 0, 0); } while (0)
; #define PG8_LDA(dst, b, h) do { _Pragma("unroll") for (int m = 0; m < 4; ++m) _Pragma("unroll") for (int k = 0; k < 2; ++k) dst[m][k] = *(const PG8_LAS bf16x8*)(lds + PG8_SA(b, h) + aoff + m * 2048 + k * 1024); } while (0)
; #define PG8_LDB(dst, b, h) do { _Pragma("unroll") for (int n = 0; n < 2; ++n) _Pragma("unroll") for (int k = 0; k < 2; ++k) dst[n][k] = *(const PG8_LAS bf16x8*)(lds + PG8_SB(b, h) + boff + n * 2048 + k * 1024); } while (0)
; #define PG8_MMA(ai, bj, At, Bt) do { __builtin_amdgcn_s_setprio(1); _Pragma("unroll") for (int m = 0; m < 4; ++m) _Pragma("unroll") for (int n = 0; n < 2; ++n) _Pragma("unroll") for (int k = 0; k < 2; ++k) \
;         acc[ai][bj][m][n] = __builtin_amdgcn_mfma_f32_16x16x32_bf16(Bt[n][k], At[m][k], acc[ai][bj][m][n], 0, 0, 0); __builtin_amdgcn_s_setprio(0); } while (0)
; #define PG8_WAIT_V(n) asm volatile("s_waitcnt vmcnt(" #n ")" ::: "memory")
; #define PG8_WAIT_L(n) asm volatile("s_waitcnt lgkmcnt(" #n ")" ::: "memory")
; #define PG8_BAR __builtin_amdgcn_s_barrier()
; #define PG8_SCHED __builtin_amdgcn_sched_barrier(0)
; template <class Epi, class Sched, bool ALIGN_EPI = false, bool SP2 = false>
; __device__ __forceinline__ void gemm_phase(PG8_LAS unsigned char* lds, const Gemm g, const Sched& S, const Epi& E) {
;     ...
;             PG8_LDB(B0, 1, 0); PG8_LDB(B1, 1, 1); PG8_SCHED; PG8_LDA(At, 1, 0); PG8_STAGE(PG8_SA(0, 1), a2 + hstep, voffA);
;             PG8_WAIT_V(8); PG8_WAIT_L(0); PG8_BAR; PG8_MMA(0, 0, At, B0); PG8_MMA(0, 1, At, B1); PG8_BAR; PG8_SCHED;
;             PG8_LDA(At, 1, 1); PG8_STAGE(PG8_SB(1, 0), b3, voffB); PG8_STAGE(PG8_SB(1, 1), b3 + hstep, voffB); PG8_STAGE(PG8_SA(1, 0), a3, voffA);
;             PG8_WAIT_V(8); PG8_WAIT_L(0); PG8_BAR; PG8_MMA(1, 0, At, B0); PG8_MMA(1, 1, At, B1); PG8_BAR; PG8_SCHED;
	s_setprio 2
	v_mfma_f32_16x16x32_bf16 v[126:129], v[130:133], v[196:199], v[126:129]
	v_mfma_f32_16x16x32_bf16 v[122:125], v[138:141], v[196:199], v[122:125]
	v_mfma_f32_16x16x32_bf16 v[110:113], v[130:133], v[204:207], v[110:113]
	v_mfma_f32_16x16x32_bf16 v[106:109], v[138:141], v[204:207], v[106:109]
	v_mfma_f32_16x16x32_bf16 v[94:97], v[130:133], v[212:215], v[94:97]
	v_mfma_f32_16x16x32_bf16 v[90:93], v[138:141], v[212:215], v[90:93]
	v_mfma_f32_16x16x32_bf16 v[78:81], v[130:133], v[224:227], v[78:81]
	v_mfma_f32_16x16x32_bf16 v[74:77], v[138:141], v[224:227], v[74:77]
	v_mfma_f32_16x16x32_bf16 v[126:129], v[134:137], v[200:203], v[126:129]
	v_mfma_f32_16x16x32_bf16 v[122:125], v[142:145], v[200:203], v[122:125]
	v_mfma_f32_16x16x32_bf16 v[110:113], v[134:137], v[208:211], v[110:113]
	v_mfma_f32_16x16x32_bf16 v[106:109], v[142:145], v[208:211], v[106:109]
	v_mfma_f32_16x16x32_bf16 v[94:97], v[134:137], v[220:223], v[94:97]
	v_mfma_f32_16x16x32_bf16 v[90:93], v[142:145], v[220:223], v[90:93]
	v_mfma_f32_16x16x32_bf16 v[78:81], v[134:137], v[228:231], v[78:81]
	v_mfma_f32_16x16x32_bf16 v[74:77], v[142:145], v[228:231], v[74:77]
	v_mfma_f32_16x16x32_bf16 v[118:121], v[162:165], v[196:199], v[118:121]
	v_mfma_f32_16x16x32_bf16 v[114:117], v[184:187], v[196:199], v[114:117]
	v_mfma_f32_16x16x32_bf16 v[102:105], v[162:165], v[204:207], v[102:105]
	v_mfma_f32_16x16x32_bf16 v[98:101], v[184:187], v[204:207], v[98:101]
	v_mfma_f32_16x16x32_bf16 v[86:89], v[162:165], v[212:215], v[86:89]
	v_mfma_f32_16x16x32_bf16 v[82:85], v[184:187], v[212:215], v[82:85]
	v_mfma_f32_16x16x32_bf16 v[70:73], v[162:165], v[224:227], v[70:73]
	v_mfma_f32_16x16x32_bf16 v[66:69], v[184:187], v[224:227], v[66:69]
	v_mfma_f32_16x16x32_bf16 v[118:121], v[180:183], v[200:203], v[118:121]
	v_mfma_f32_16x16x32_bf16 v[114:117], v[188:191], v[200:203], v[114:117]
	v_mfma_f32_16x16x32_bf16 v[102:105], v[180:183], v[208:211], v[102:105]
	v_mfma_f32_16x16x32_bf16 v[98:101], v[188:191], v[208:211], v[98:101]
	v_mfma_f32_16x16x32_bf16 v[86:89], v[180:183], v[220:223], v[86:89]
	v_mfma_f32_16x16x32_bf16 v[82:85], v[188:191], v[220:223], v[82:85]
	v_mfma_f32_16x16x32_bf16 v[70:73], v[180:183], v[228:231], v[70:73]
	v_mfma_f32_16x16x32_bf16 v[66:69], v[188:191], v[228:231], v[66:69]
	s_setprio 0
	ds_read_b128 v[196:199], v179 offset:49152
	ds_read_b128 v[200:203], v179 offset:50176
	ds_read_b128 v[204:207], v179 offset:51200
	ds_read_b128 v[208:211], v179 offset:52224
	ds_read_b128 v[212:215], v179 offset:53248
	ds_read_b128 v[220:223], v179 offset:54272
	ds_read_b128 v[224:227], v179 offset:55296
	ds_read_b128 v[228:231], v179 offset:56320
	s_add_u32 s60, s40, 0x80
	s_addc_u32 s61, s41, 0
	s_add_u32 vcc_lo, s60, 0x100000
	s_addc_u32 vcc_hi, s61, 0
	s_add_i32 m0, s24, 0x18000
	s_nop 0
	global_load_lds_dwordx4 v148, s[60:61]
	s_add_i32 m0, s24, 0x1a000
	s_nop 0
	global_load_lds_dwordx4 v152, s[60:61]
	s_add_i32 m0, s24, 0x1c000
	s_nop 0
	global_load_lds_dwordx4 v148, vcc
	s_add_i32 m0, s24, 0x1e000
	s_nop 0
	global_load_lds_dwordx4 v152, vcc
	s_add_u32 s60, s42, 0x80
	s_addc_u32 s61, s43, 0
	s_add_i32 m0, s24, 0x8000
	s_nop 0
	global_load_lds_dwordx4 v146, s[60:61]
	s_add_i32 m0, s24, 0xa000
	s_nop 0
	global_load_lds_dwordx4 v150, s[60:61]
	s_sleep 1
	s_waitcnt lgkmcnt(0)
	s_waitcnt vmcnt(8)
	s_barrier
	s_setprio 2
	v_mfma_f32_16x16x32_bf16 v[62:65], v[130:133], v[196:199], v[62:65]
	v_mfma_f32_16x16x32_bf16 v[58:61], v[138:141], v[196:199], v[58:61]
	v_mfma_f32_16x16x32_bf16 v[46:49], v[130:133], v[204:207], v[46:49]
	v_mfma_f32_16x16x32_bf16 v[42:45], v[138:141], v[204:207], v[42:45]
	v_mfma_f32_16x16x32_bf16 v[30:33], v[130:133], v[212:215], v[30:33]
	v_mfma_f32_16x16x32_bf16 v[26:29], v[138:141], v[212:215], v[26:29]
	v_mfma_f32_16x16x32_bf16 v[14:17], v[130:133], v[224:227], v[14:17]
	v_mfma_f32_16x16x32_bf16 v[10:13], v[138:141], v[224:227], v[10:13]
	v_mfma_f32_16x16x32_bf16 v[62:65], v[134:137], v[200:203], v[62:65]
	v_mfma_f32_16x16x32_bf16 v[58:61], v[142:145], v[200:203], v[58:61]
	v_mfma_f32_16x16x32_bf16 v[46:49], v[134:137], v[208:211], v[46:49]
	v_mfma_f32_16x16x32_bf16 v[42:45], v[142:145], v[208:211], v[42:45]
	v_mfma_f32_16x16x32_bf16 v[30:33], v[134:137], v[220:223], v[30:33]
	v_mfma_f32_16x16x32_bf16 v[26:29], v[142:145], v[220:223], v[26:29]
	v_mfma_f32_16x16x32_bf16 v[14:17], v[134:137], v[228:231], v[14:17]
	v_mfma_f32_16x16x32_bf16 v[10:13], v[142:145], v[228:231], v[10:13]
	v_mfma_f32_16x16x32_bf16 v[54:57], v[162:165], v[196:199], v[54:57]
	v_mfma_f32_16x16x32_bf16 v[50:53], v[184:187], v[196:199], v[50:53]
	v_mfma_f32_16x16x32_bf16 v[38:41], v[162:165], v[204:207], v[38:41]
	v_mfma_f32_16x16x32_bf16 v[34:37], v[184:187], v[204:207], v[34:37]
	v_mfma_f32_16x16x32_bf16 v[22:25], v[162:165], v[212:215], v[22:25]
	v_mfma_f32_16x16x32_bf16 v[18:21], v[184:187], v[212:215], v[18:21]
	v_mfma_f32_16x16x32_bf16 v[6:9], v[162:165], v[224:227], v[6:9]
	v_mfma_f32_16x16x32_bf16 v[2:5], v[184:187], v[224:227], v[2:5]
	v_mfma_f32_16x16x32_bf16 v[54:57], v[180:183], v[200:203], v[54:57]
	v_mfma_f32_16x16x32_bf16 v[50:53], v[188:191], v[200:203], v[50:53]
	v_mfma_f32_16x16x32_bf16 v[38:41], v[180:183], v[208:211], v[38:41]
	v_mfma_f32_16x16x32_bf16 v[34:37], v[188:191], v[208:211], v[34:37]
	v_mfma_f32_16x16x32_bf16 v[22:25], v[180:183], v[220:223], v[22:25]
	v_mfma_f32_16x16x32_bf16 v[18:21], v[188:191], v[220:223], v[18:21]
	v_mfma_f32_16x16x32_bf16 v[6:9], v[180:183], v[228:231], v[6:9]
	v_mfma_f32_16x16x32_bf16 v[2:5], v[188:191], v[228:231], v[2:5]
	s_setprio 0
	s_add_i32 s58, s58, 2
	s_add_u32 s36, s36, 0x100
	s_addc_u32 s37, s37, 0
	s_add_u32 s56, s56, 0x100
	s_addc_u32 s57, s57, 0
	s_cmp_gt_u32 s58, 61
	s_cbranch_scc0 .Lf1_h1

; #define PG8_STAGE(bufoff, gbase, voff) do { _Pragma("unroll") for (int _i = 0; _i < 2; ++_i) \
;         __builtin_amdgcn_global_load_lds((const unsigned*)((const char*)(gbase) + (voff)[_i]), (PG8_LAS unsigned*)(lds + (bufoff) + ldsw + _i * 8192), 16, 0, 0); } while (0)
; #define PG8_LDA(dst, b, h) do { _Pragma("unroll") for (int m = 0; m < 4; ++m) _Pragma("unroll") for (int k = 0; k < 2; ++k) dst[m][k] = *(const PG8_LAS bf16x8*)(lds + PG8_SA(b, h) + aoff + m * 2048 + k * 1024); } while (0)
; #define PG8_LDB(dst, b, h) do { _Pragma("unroll") for (int n = 0; n < 2; ++n) _Pragma("unroll") for (int k = 0; k < 2; ++k) dst[n][k] = *(const PG8_LAS bf16x8*)(lds + PG8_SB(b, h) + boff + n * 2048 + k * 1024); } while (0)
; #define PG8_MMA(ai, bj, At, Bt) do { __builtin_amdgcn_s_setprio(1); _Pragma("unroll") for (int m = 0; m < 4; ++m) _Pragma("unroll") for (int n = 0; n < 2; ++n) _Pragma("unroll") for (int k = 0; k < 2; ++k) \
;         acc[ai][bj][m][n] = __builtin_amdgcn_mfma_f32_16x16x32_bf16(Bt[n][k], At[m][k], acc[ai][bj][m][n], 0, 0, 0); __builtin_amdgcn_s_setprio(0); } while (0)
; #define PG8_WAIT_V(n) asm volatile("s_waitcnt vmcnt(" #n ")" ::: "memory")
; #define PG8_WAIT_L(n) asm volatile("s_waitcnt lgkmcnt(" #n ")" ::: "memory")
; #define PG8_BAR __builtin_amdgcn_s_barrier()
; #define PG8_SCHED __builtin_amdgcn_sched_barrier(0)
; template <class Epi, class Sched, bool ALIGN_EPI = false, bool SP2 = false>
; __device__ __forceinline__ void gemm_phase(PG8_LAS unsigned char* lds, const Gemm g, const Sched& S, const Epi& E) {
;     ...
;             PG8_LDB(B0, 0, 0); PG8_LDB(B1, 0, 1); PG8_SCHED; PG8_LDA(At, 0, 0); PG8_STAGE(PG8_SA(1, 1), a1 + hstep, voffA);
;             PG8_WAIT_V(8); PG8_WAIT_L(0); PG8_BAR; PG8_MMA(0, 0, At, B0); PG8_MMA(0, 1, At, B1); PG8_BAR; PG8_SCHED;
;             PG8_LDA(At, 0, 1); PG8_STAGE(PG8_SB(0, 0), b2, voffB); PG8_STAGE(PG8_SB(0, 1), b2 + hstep, voffB); PG8_STAGE(PG8_SA(0, 0), a2, voffA);
;             PG8_WAIT_V(8); PG8_WAIT_L(0); PG8_BAR; PG8_MMA(1, 0, At, B0); PG8_MMA(1, 1, At, B1); PG8_BAR; PG8_SCHED;
.Lf2_h1:
	ds_read_b128 v[128:131], v156
	ds_read_b128 v[132:135], v156 offset:1024
	ds_read_b128 v[150:153], v156 offset:2048
	ds_read_b128 v[162:165], v156 offset:3072
	ds_read_b128 v[166:169], v157
	ds_read_b128 v[170:173], v157 offset:1024
	ds_read_b128 v[174:177], v157 offset:2048
	ds_read_b128 v[178:181], v157 offset:3072
	s_add_u32 s20, s18, 0xffbfc080
	s_addc_u32 s21, s19, -1
	s_cmpk_eq_i32 s59, 0xfc
	s_cselect_b32 s23, s7, s21
	s_cselect_b32 s22, s6, s20
	s_cselect_b32 s21, s17, s58
	s_cselect_b32 s20, s16, s57
	ds_read_b128 v[182:185], v158
	ds_read_b128 v[186:189], v158 offset:1024
	ds_read_b128 v[190:193], v158 offset:2048
	ds_read_b128 v[194:197], v158 offset:3072
	ds_read_b128 v[198:201], v158 offset:4096
	ds_read_b128 v[202:205], v158 offset:5120
	ds_read_b128 v[206:209], v158 offset:6144
	ds_read_b128 v[210:213], v158 offset:7168
	s_add_i32 m0, s24, 0xc000
	s_nop 0
	global_load_lds_dwordx4 v136, s[18:19]
	s_add_i32 m0, s24, 0xe000
	s_nop 0
	global_load_lds_dwordx4 v140, s[18:19]
	s_sleep 1
	s_waitcnt lgkmcnt(0)
	s_waitcnt vmcnt(8)
	s_barrier
	s_setprio 2
	v_mfma_f32_16x16x32_bf16 v[124:127], v[128:131], v[182:185], v[124:127]
	v_mfma_f32_16x16x32_bf16 v[120:123], v[150:153], v[182:185], v[120:123]
	v_mfma_f32_16x16x32_bf16 v[116:119], v[128:131], v[190:193], v[116:119]
	v_mfma_f32_16x16x32_bf16 v[112:115], v[150:153], v[190:193], v[112:115]
	v_mfma_f32_16x16x32_bf16 v[108:111], v[128:131], v[198:201], v[108:111]
	v_mfma_f32_16x16x32_bf16 v[104:107], v[150:153], v[198:201], v[104:107]
	v_mfma_f32_16x16x32_bf16 v[100:103], v[128:131], v[206:209], v[100:103]
	v_mfma_f32_16x16x32_bf16 v[96:99], v[150:153], v[206:209], v[96:99]
	v_mfma_f32_16x16x32_bf16 v[124:127], v[132:135], v[186:189], v[124:127]
	v_mfma_f32_16x16x32_bf16 v[120:123], v[162:165], v[186:189], v[120:123]
	v_mfma_f32_16x16x32_bf16 v[116:119], v[132:135], v[194:197], v[116:119]
	v_mfma_f32_16x16x32_bf16 v[112:115], v[162:165], v[194:197], v[112:115]
	v_mfma_f32_16x16x32_bf16 v[108:111], v[132:135], v[202:205], v[108:111]
	v_mfma_f32_16x16x32_bf16 v[104:107], v[162:165], v[202:205], v[104:107]
	v_mfma_f32_16x16x32_bf16 v[100:103], v[132:135], v[210:213], v[100:103]
	v_mfma_f32_16x16x32_bf16 v[96:99], v[162:165], v[210:213], v[96:99]
	v_mfma_f32_16x16x32_bf16 v[68:71], v[166:169], v[182:185], v[68:71]
	v_mfma_f32_16x16x32_bf16 v[64:67], v[174:177], v[182:185], v[64:67]
	v_mfma_f32_16x16x32_bf16 v[52:55], v[166:169], v[190:193], v[52:55]
	v_mfma_f32_16x16x32_bf16 v[48:51], v[174:177], v[190:193], v[48:51]
	v_mfma_f32_16x16x32_bf16 v[44:47], v[166:169], v[198:201], v[44:47]
	v_mfma_f32_16x16x32_bf16 v[40:43], v[174:177], v[198:201], v[40:43]
	v_mfma_f32_16x16x32_bf16 v[36:39], v[166:169], v[206:209], v[36:39]
	v_mfma_f32_16x16x32_bf16 v[32:35], v[174:177], v[206:209], v[32:35]
	v_mfma_f32_16x16x32_bf16 v[68:71], v[170:173], v[186:189], v[68:71]
	v_mfma_f32_16x16x32_bf16 v[64:67], v[178:181], v[186:189], v[64:67]
	v_mfma_f32_16x16x32_bf16 v[52:55], v[170:173], v[194:197], v[52:55]
	v_mfma_f32_16x16x32_bf16 v[48:51], v[178:181], v[194:197], v[48:51]
	v_mfma_f32_16x16x32_bf16 v[44:47], v[170:173], v[202:205], v[44:47]
	v_mfma_f32_16x16x32_bf16 v[40:43], v[178:181], v[202:205], v[40:43]
	v_mfma_f32_16x16x32_bf16 v[36:39], v[170:173], v[210:213], v[36:39]
	v_mfma_f32_16x16x32_bf16 v[32:35], v[178:181], v[210:213], v[32:35]
	s_setprio 0
	ds_read_b128 v[182:185], v158 offset:16384
	ds_read_b128 v[186:189], v158 offset:17408
	ds_read_b128 v[190:193], v158 offset:18432
	ds_read_b128 v[194:197], v158 offset:19456
	ds_read_b128 v[198:201], v158 offset:20480
	ds_read_b128 v[202:205], v158 offset:21504
	ds_read_b128 v[206:209], v158 offset:22528
	ds_read_b128 v[210:213], v158 offset:23552
	s_add_u32 vcc_lo, s20, 0x404000
	s_addc_u32 vcc_hi, s21, 0
	s_add_i32 m0, s24, 0x10000
	s_nop 0
	global_load_lds_dwordx4 v138, s[20:21]
	s_add_i32 m0, s24, 0x12000
	s_nop 0
	global_load_lds_dwordx4 v142, s[20:21]
	s_add_i32 m0, s24, 0x14000
	s_nop 0
	global_load_lds_dwordx4 v138, vcc
	s_add_i32 m0, s24, 0x16000
	s_nop 0
	global_load_lds_dwordx4 v142, vcc
	s_mov_b32 m0, s24
	s_nop 0
	global_load_lds_dwordx4 v136, s[22:23]
	s_add_i32 m0, s24, 0x2000
	s_nop 0
	global_load_lds_dwordx4 v140, s[22:23]
	s_sleep 1
	s_waitcnt lgkmcnt(0)
	s_waitcnt vmcnt(8)
	s_barrier
; #define PG8_STAGE(bufoff, gbase, voff) do { _Pragma("unroll") for (int _i = 0; _i < 2; ++_i) \
;         __builtin_amdgcn_global_load_lds((const unsigned*)((const char*)(gbase) + (voff)[_i]), (PG8_LAS unsigned*)(lds + (bufoff) + ldsw + _i * 8192), 16, 0, 0); } while (0)
; #define PG8_LDA(dst, b, h) do { _Pragma("unroll") for (int m = 0; m < 4; ++m) _Pragma("unroll") for (int k = 0; k < 2; ++k) dst[m][k] = *(const PG8_LAS bf16x8*)(lds + PG8_SA(b, h) + aoff + m * 2048 + k * 1024); } while (0)
; #define PG8_LDB(dst, b, h) do { _Pragma("unroll") for (int n = 0; n < 2; ++n) _Pragma("unroll") for (int k = 0; k < 2; ++k) dst[n][k] = *(const PG8_LAS bf16x8*)(lds + PG8_SB(b, h) + boff + n * 2048 + k * 1024); } while (0)
; #define PG8_MMA(ai, bj, At, Bt) do { __builtin_amdgcn_s_setprio(1); _Pragma("unroll") for (int m = 0; m < 4; ++m) _Pragma("unroll") for (int n = 0; n < 2; ++n) _Pragma("unroll") for (int k = 0; k < 2; ++k) \
;         acc[ai][bj][m][n] = __builtin_amdgcn_mfma_f32_16x16x32_bf16(Bt[n][k], At[m][k], acc[ai][bj][m][n], 0, 0, 0); __builtin_amdgcn_s_setprio(0); } while (0)
; #define PG8_WAIT_V(n) asm volatile("s_waitcnt vmcnt(" #n ")" ::: "memory")
; #define PG8_WAIT_L(n) asm volatile("s_waitcnt lgkmcnt(" #n ")" ::: "memory")
; #define PG8_BAR __builtin_amdgcn_s_barrier()
; #define PG8_SCHED __builtin_amdgcn_sched_barrier(0)
; template <class Epi, class Sched, bool ALIGN_EPI = false, bool SP2 = false>
; __device__ __forceinline__ void gemm_phase(PG8_LAS unsigned char* lds, const Gemm g, const Sched& S, const Epi& E) {
;     ...
;             PG8_WAIT_V(8); PG8_WAIT_L(0); PG8_BAR; PG8_MMA(0, 0, At, B0); PG8_MMA(0, 1, At, B1); PG8_BAR; PG8_SCHED;
;             PG8_LDA(At, 0, 1); PG8_STAGE(PG8_SB(0, 0), b2, voffB); PG8_STAGE(PG8_SB(0, 1), b2 + hstep, voffB); PG8_STAGE(PG8_SA(0, 0), a2, voffA);
;             PG8_WAIT_V(8); PG8_WAIT_L(0); PG8_BAR; PG8_MMA(1, 0, At, B0); PG8_MMA(1, 1, At, B1); PG8_BAR; PG8_SCHED;
;             PG8_LDB(B0, 1, 0); PG8_LDB(B1, 1, 1); PG8_SCHED; PG8_LDA(At, 1, 0); PG8_STAGE(PG8_SA(0, 1), a2 + hstep, voffA);
;             PG8_WAIT_V(8); PG8_WAIT_L(0); PG8_BAR; PG8_MMA(0, 0, At, B0); PG8_MMA(0, 1, At, B1); PG8_BAR; PG8_SCHED;
	s_setprio 2
	v_mfma_f32_16x16x32_bf16 v[92:95], v[128:131], v[182:185], v[92:95]
	v_mfma_f32_16x16x32_bf16 v[88:91], v[150:153], v[182:185], v[88:91]
	v_mfma_f32_16x16x32_bf16 v[84:87], v[128:131], v[190:193], v[84:87]
	v_mfma_f32_16x16x32_bf16 v[80:83], v[150:153], v[190:193], v[80:83]
	v_mfma_f32_16x16x32_bf16 v[76:79], v[128:131], v[198:201], v[76:79]
	v_mfma_f32_16x16x32_bf16 v[72:75], v[150:153], v[198:201], v[72:75]
	v_mfma_f32_16x16x32_bf16 v[60:63], v[128:131], v[206:209], v[60:63]
	v_mfma_f32_16x16x32_bf16 v[56:59], v[150:153], v[206:209], v[56:59]
	v_mfma_f32_16x16x32_bf16 v[92:95], v[132:135], v[186:189], v[92:95]
	v_mfma_f32_16x16x32_bf16 v[88:91], v[162:165], v[186:189], v[88:91]
	v_mfma_f32_16x16x32_bf16 v[84:87], v[132:135], v[194:197], v[84:87]
	v_mfma_f32_16x16x32_bf16 v[80:83], v[162:165], v[194:197], v[80:83]
	v_mfma_f32_16x16x32_bf16 v[76:79], v[132:135], v[202:205], v[76:79]
	v_mfma_f32_16x16x32_bf16 v[72:75], v[162:165], v[202:205], v[72:75]
	v_mfma_f32_16x16x32_bf16 v[60:63], v[132:135], v[210:213], v[60:63]
	v_mfma_f32_16x16x32_bf16 v[56:59], v[162:165], v[210:213], v[56:59]
	v_mfma_f32_16x16x32_bf16 v[28:31], v[166:169], v[182:185], v[28:31]
	v_mfma_f32_16x16x32_bf16 v[24:27], v[174:177], v[182:185], v[24:27]
	v_mfma_f32_16x16x32_bf16 v[20:23], v[166:169], v[190:193], v[20:23]
	v_mfma_f32_16x16x32_bf16 v[16:19], v[174:177], v[190:193], v[16:19]
	v_mfma_f32_16x16x32_bf16 v[12:15], v[166:169], v[198:201], v[12:15]
	v_mfma_f32_16x16x32_bf16 v[8:11], v[174:177], v[198:201], v[8:11]
	v_mfma_f32_16x16x32_bf16 v[4:7], v[166:169], v[206:209], v[4:7]
	v_mfma_f32_16x16x32_bf16 v[0:3], v[174:177], v[206:209], v[0:3]
	v_mfma_f32_16x16x32_bf16 v[28:31], v[170:173], v[186:189], v[28:31]
	v_mfma_f32_16x16x32_bf16 v[24:27], v[178:181], v[186:189], v[24:27]
	v_mfma_f32_16x16x32_bf16 v[20:23], v[170:173], v[194:197], v[20:23]
	v_mfma_f32_16x16x32_bf16 v[16:19], v[178:181], v[194:197], v[16:19]
	v_mfma_f32_16x16x32_bf16 v[12:15], v[170:173], v[202:205], v[12:15]
	v_mfma_f32_16x16x32_bf16 v[8:11], v[178:181], v[202:205], v[8:11]
	v_mfma_f32_16x16x32_bf16 v[4:7], v[170:173], v[210:213], v[4:7]
	v_mfma_f32_16x16x32_bf16 v[0:3], v[178:181], v[210:213], v[0:3]
	s_setprio 0
	ds_read_b128 v[128:131], v159
	ds_read_b128 v[132:135], v159 offset:1024
	ds_read_b128 v[150:153], v159 offset:2048
	ds_read_b128 v[162:165], v159 offset:3072
	ds_read_b128 v[166:169], v160
	ds_read_b128 v[170:173], v160 offset:1024
	ds_read_b128 v[174:177], v160 offset:2048
	ds_read_b128 v[178:181], v160 offset:3072
	ds_read_b128 v[182:185], v158 offset:32768
	ds_read_b128 v[186:189], v158 offset:33792
	ds_read_b128 v[190:193], v158 offset:34816
	ds_read_b128 v[194:197], v158 offset:35840
	ds_read_b128 v[198:201], v158 offset:36864
	ds_read_b128 v[202:205], v158 offset:37888
	ds_read_b128 v[206:209], v158 offset:38912
	ds_read_b128 v[210:213], v158 offset:39936
	s_add_u32 vcc_lo, s22, 0x404000
	s_addc_u32 vcc_hi, s23, 0
	s_add_i32 m0, s24, 0x4000
	s_nop 0
	global_load_lds_dwordx4 v136, vcc
	s_add_i32 m0, s24, 0x6000
	s_nop 0
	global_load_lds_dwordx4 v140, vcc
	s_sleep 1
	s_waitcnt lgkmcnt(0)
	s_waitcnt vmcnt(8)
	s_barrier
; #define PG8_STAGE(bufoff, gbase, voff) do { _Pragma("unroll") for (int _i = 0; _i < 2; ++_i) \
;         __builtin_amdgcn_global_load_lds((const unsigned*)((const char*)(gbase) + (voff)[_i]), (PG8_LAS unsigned*)(lds + (bufoff) + ldsw + _i * 8192), 16, 0, 0); } while (0)
; #define PG8_LDA(dst, b, h) do { _Pragma("unroll") for (int m = 0; m < 4; ++m) _Pragma("unroll") for (int k = 0; k < 2; ++k) dst[m][k] = *(const PG8_LAS bf16x8*)(lds + PG8_SA(b, h) + aoff + m * 2048 + k * 1024); } while (0)
; #define PG8_LDB(dst, b, h) do { _Pragma("unroll") for (int n = 0; n < 2; ++n) _Pragma("unroll") for (int k = 0; k < 2; ++k) dst[n][k] = *(const PG8_LAS bf16x8*)(lds + PG8_SB(b, h) + boff + n * 2048 + k * 1024); } while (0)
; #define PG8_MMA(ai, bj, At, Bt) do { __builtin_amdgcn_s_setprio(1); _Pragma("unroll") for (int m = 0; m < 4; ++m) _Pragma("unroll") for (int n = 0; n < 2; ++n) _Pragma("unroll") for (int k = 0; k < 2; ++k) \
;         acc[ai][bj][m][n] = __builtin_amdgcn_mfma_f32_16x16x32_bf16(Bt[n][k], At[m][k], acc[ai][bj][m][n], 0, 0, 0); __builtin_amdgcn_s_setprio(0); } while (0)
; #define PG8_BAR __builtin_amdgcn_s_barrier()
; template <class Epi, class Sched, bool ALIGN_EPI = false, bool SP2 = false>
; __device__ __forceinline__ void gemm_phase(PG8_LAS unsigned char* lds, const Gemm g, const Sched& S, const Epi& E) {
;     ...
;             if constexpr (SP2) {
;             PG8_LDB(B0, 0, 0); PG8_LDB(B1, 0, 1); PG8_SCHED; PG8_LDA(At, 0, 0); PG8_STAGE(PG8_SA(1, 1), a1 + hstep, voffA);
;             PG8_WAIT_V(8); PG8_WAIT_L(0); PG8_BAR; PG8_MMA(0, 0, At, B0); PG8_MMA(0, 1, At, B1); PG8_BAR; PG8_SCHED;
;             PG8_LDA(At, 0, 1); PG8_STAGE(PG8_SB(0, 0), b2, voffB); PG8_STAGE(PG8_SB(0, 1), b2 + hstep, voffB); PG8_STAGE(PG8_SA(0, 0), a2, voffA);
;             PG8_WAIT_V(8); PG8_WAIT_L(0); PG8_BAR; PG8_MMA(1, 0, At, B0); PG8_MMA(1, 1, At, B1); PG8_BAR; PG8_SCHED;
;             PG8_LDB(B0, 1, 0); PG8_LDB(B1, 1, 1); PG8_SCHED; PG8_LDA(At, 1, 0); PG8_STAGE(PG8_SA(0, 1), a2 + hstep, voffA);
;             PG8_WAIT_V(8); PG8_WAIT_L(0); PG8_BAR; PG8_MMA(0, 0, At, B0); PG8_MMA(0, 1, At, B1); PG8_BAR; PG8_SCHED;
;             PG8_LDA(At, 1, 1); PG8_STAGE(PG8_SB(1, 0), b3, voffB); PG8_STAGE(PG8_SB(1, 1), b3 + hstep, voffB); PG8_STAGE(PG8_SA(1, 0), a3, voffA);
;             PG8_WAIT_V(8); PG8_WAIT_L(0); PG8_BAR; PG8_MMA(1, 0, At, B0); PG8_MMA(1, 1, At, B1); PG8_BAR; PG8_SCHED;
	s_setprio 2
	v_mfma_f32_16x16x32_bf16 v[124:127], v[128:131], v[182:185], v[124:127]
	v_mfma_f32_16x16x32_bf16 v[120:123], v[150:153], v[182:185], v[120:123]
	v_mfma_f32_16x16x32_bf16 v[116:119], v[128:131], v[190:193], v[116:119]
	v_mfma_f32_16x16x32_bf16 v[112:115], v[150:153], v[190:193], v[112:115]
	v_mfma_f32_16x16x32_bf16 v[108:111], v[128:131], v[198:201], v[108:111]
	v_mfma_f32_16x16x32_bf16 v[104:107], v[150:153], v[198:201], v[104:107]
	v_mfma_f32_16x16x32_bf16 v[100:103], v[128:131], v[206:209], v[100:103]
	v_mfma_f32_16x16x32_bf16 v[96:99], v[150:153], v[206:209], v[96:99]
	v_mfma_f32_16x16x32_bf16 v[124:127], v[132:135], v[186:189], v[124:127]
	v_mfma_f32_16x16x32_bf16 v[120:123], v[162:165], v[186:189], v[120:123]
	v_mfma_f32_16x16x32_bf16 v[116:119], v[132:135], v[194:197], v[116:119]
	v_mfma_f32_16x16x32_bf16 v[112:115], v[162:165], v[194:197], v[112:115]
	v_mfma_f32_16x16x32_bf16 v[108:111], v[132:135], v[202:205], v[108:111]
	v_mfma_f32_16x16x32_bf16 v[104:107], v[162:165], v[202:205], v[104:107]
	v_mfma_f32_16x16x32_bf16 v[100:103], v[132:135], v[210:213], v[100:103]
	v_mfma_f32_16x16x32_bf16 v[96:99], v[162:165], v[210:213], v[96:99]
	v_mfma_f32_16x16x32_bf16 v[68:71], v[166:169], v[182:185], v[68:71]
	v_mfma_f32_16x16x32_bf16 v[64:67], v[174:177], v[182:185], v[64:67]
	v_mfma_f32_16x16x32_bf16 v[52:55], v[166:169], v[190:193], v[52:55]
	v_mfma_f32_16x16x32_bf16 v[48:51], v[174:177], v[190:193], v[48:51]
	v_mfma_f32_16x16x32_bf16 v[44:47], v[166:169], v[198:201], v[44:47]
	v_mfma_f32_16x16x32_bf16 v[40:43], v[174:177], v[198:201], v[40:43]
	v_mfma_f32_16x16x32_bf16 v[36:39], v[166:169], v[206:209], v[36:39]
	v_mfma_f32_16x16x32_bf16 v[32:35], v[174:177], v[206:209], v[32:35]
	v_mfma_f32_16x16x32_bf16 v[68:71], v[170:173], v[186:189], v[68:71]
	v_mfma_f32_16x16x32_bf16 v[64:67], v[178:181], v[186:189], v[64:67]
	v_mfma_f32_16x16x32_bf16 v[52:55], v[170:173], v[194:197], v[52:55]
	v_mfma_f32_16x16x32_bf16 v[48:51], v[178:181], v[194:197], v[48:51]
	v_mfma_f32_16x16x32_bf16 v[44:47], v[170:173], v[202:205], v[44:47]
	v_mfma_f32_16x16x32_bf16 v[40:43], v[178:181], v[202:205], v[40:43]
	v_mfma_f32_16x16x32_bf16 v[36:39], v[170:173], v[210:213], v[36:39]
	v_mfma_f32_16x16x32_bf16 v[32:35], v[178:181], v[210:213], v[32:35]
	s_setprio 0
	ds_read_b128 v[182:185], v158 offset:49152
	ds_read_b128 v[186:189], v158 offset:50176
	ds_read_b128 v[190:193], v158 offset:51200
	ds_read_b128 v[194:197], v158 offset:52224
	ds_read_b128 v[198:201], v158 offset:53248
	ds_read_b128 v[202:205], v158 offset:54272
	ds_read_b128 v[206:209], v158 offset:55296
	ds_read_b128 v[210:213], v158 offset:56320
	s_add_u32 s60, s20, 0x80
	s_addc_u32 s61, s21, 0
	s_add_u32 vcc_lo, s60, 0x404000
	s_addc_u32 vcc_hi, s61, 0
	s_add_i32 m0, s24, 0x18000
	s_nop 0
	global_load_lds_dwordx4 v138, s[60:61]
	s_add_i32 m0, s24, 0x1a000
	s_nop 0
	global_load_lds_dwordx4 v142, s[60:61]
	s_add_i32 m0, s24, 0x1c000
	s_nop 0
	global_load_lds_dwordx4 v138, vcc
	s_add_i32 m0, s24, 0x1e000
	s_nop 0
	global_load_lds_dwordx4 v142, vcc
	s_add_u32 s60, s22, 0x80
	s_addc_u32 s61, s23, 0
	s_add_i32 m0, s24, 0x8000
	s_nop 0
	global_load_lds_dwordx4 v136, s[60:61]
	s_add_i32 m0, s24, 0xa000
	s_nop 0
	global_load_lds_dwordx4 v140, s[60:61]
	s_sleep 1
	s_waitcnt lgkmcnt(0)
	s_waitcnt vmcnt(8)
	s_barrier
	s_setprio 2
	v_mfma_f32_16x16x32_bf16 v[92:95], v[128:131], v[182:185], v[92:95]
	v_mfma_f32_16x16x32_bf16 v[88:91], v[150:153], v[182:185], v[88:91]
	v_mfma_f32_16x16x32_bf16 v[84:87], v[128:131], v[190:193], v[84:87]
	v_mfma_f32_16x16x32_bf16 v[80:83], v[150:153], v[190:193], v[80:83]
	v_mfma_f32_16x16x32_bf16 v[76:79], v[128:131], v[198:201], v[76:79]
	v_mfma_f32_16x16x32_bf16 v[72:75], v[150:153], v[198:201], v[72:75]
	v_mfma_f32_16x16x32_bf16 v[60:63], v[128:131], v[206:209], v[60:63]
	v_mfma_f32_16x16x32_bf16 v[56:59], v[150:153], v[206:209], v[56:59]
	v_mfma_f32_16x16x32_bf16 v[92:95], v[132:135], v[186:189], v[92:95]
	v_mfma_f32_16x16x32_bf16 v[88:91], v[162:165], v[186:189], v[88:91]
	v_mfma_f32_16x16x32_bf16 v[84:87], v[132:135], v[194:197], v[84:87]
	v_mfma_f32_16x16x32_bf16 v[80:83], v[162:165], v[194:197], v[80:83]
	v_mfma_f32_16x16x32_bf16 v[76:79], v[132:135], v[202:205], v[76:79]
	v_mfma_f32_16x16x32_bf16 v[72:75], v[162:165], v[202:205], v[72:75]
	v_mfma_f32_16x16x32_bf16 v[60:63], v[132:135], v[210:213], v[60:63]
	v_mfma_f32_16x16x32_bf16 v[56:59], v[162:165], v[210:213], v[56:59]
	v_mfma_f32_16x16x32_bf16 v[28:31], v[166:169], v[182:185], v[28:31]
	v_mfma_f32_16x16x32_bf16 v[24:27], v[174:177], v[182:185], v[24:27]
	v_mfma_f32_16x16x32_bf16 v[20:23], v[166:169], v[190:193], v[20:23]
	v_mfma_f32_16x16x32_bf16 v[16:19], v[174:177], v[190:193], v[16:19]
	v_mfma_f32_16x16x32_bf16 v[12:15], v[166:169], v[198:201], v[12:15]
	v_mfma_f32_16x16x32_bf16 v[8:11], v[174:177], v[198:201], v[8:11]
	v_mfma_f32_16x16x32_bf16 v[4:7], v[166:169], v[206:209], v[4:7]
	v_mfma_f32_16x16x32_bf16 v[0:3], v[174:177], v[206:209], v[0:3]
	v_mfma_f32_16x16x32_bf16 v[28:31], v[170:173], v[186:189], v[28:31]
	v_mfma_f32_16x16x32_bf16 v[24:27], v[178:181], v[186:189], v[24:27]
	v_mfma_f32_16x16x32_bf16 v[20:23], v[170:173], v[194:197], v[20:23]
	v_mfma_f32_16x16x32_bf16 v[16:19], v[178:181], v[194:197], v[16:19]
	v_mfma_f32_16x16x32_bf16 v[12:15], v[170:173], v[202:205], v[12:15]
	v_mfma_f32_16x16x32_bf16 v[8:11], v[178:181], v[202:205], v[8:11]
	v_mfma_f32_16x16x32_bf16 v[4:7], v[170:173], v[210:213], v[4:7]
	v_mfma_f32_16x16x32_bf16 v[0:3], v[178:181], v[210:213], v[0:3]
	s_setprio 0
	s_add_i32 s59, s59, 2
	s_add_u32 s18, s18, 0x100
	s_addc_u32 s19, s19, 0
	s_add_u32 s57, s57, 0x100
	s_addc_u32 s58, s58, 0
	s_cmpk_gt_u32 s59, 0xfd
	s_cbranch_scc0 .Lf2_h1
